# dil attention restructure: all 3-4 key tiles staged up front into 3 LDS stages, per-wave 3 back-to-back tiles with 2 interior barriers (was 4 barrier-stepped iterations)
# baseline (speedup 1.0000x reference)
.LBB0_286:
	s_add_i32 s2, s14, s55
	s_cmpk_gt_i32 s2, 0x7ff
	s_mov_b64 s[0:1], -1
	s_cbranch_scc1 .LBB0_285
	s_and_b32 s0, s2, 31
	v_mov_b32_e32 v4, v194
	s_ashr_i32 s6, s2, 8
	s_and_b32 s8, s0, s22
	s_lshr_b32 s2, s2, 4
	v_bfe_u32 v5, v4, 6, 2
	s_lshr_b32 s1, s0, s21
	s_lshl_b32 s0, s8, 7
	v_and_b32_e32 v2, 31, v4
	v_ashrrev_i32_e32 v18, 8, v4
	s_and_b32 s2, s2, 14
	v_lshlrev_b32_e32 v3, 5, v5
	s_ashr_i32 s7, s6, 31
	v_add_u32_e32 v126, s2, v18
	v_or3_b32 v0, v3, s0, v2
	s_lshl_b64 s[2:3], s[6:7], 12
	v_lshlrev_b32_e32 v0, s18, v0
	s_or_b32 s2, s2, s1
	v_lshl_add_u64 v[122:123], s[2:3], 0, v[0:1]
	s_mul_i32 s1, s3, 0x1800
	s_mul_hi_u32 s3, s2, 0x1800
	v_lshlrev_b32_e32 v124, 6, v126
	s_add_i32 s3, s3, s1
	s_mul_i32 s1, s2, 0x1800
	v_ashrrev_i32_e32 v125, 31, v124
	s_add_u32 s2, s56, s1
	v_lshlrev_b64 v[10:11], 1, v[124:125]
	s_addc_u32 s3, s57, s3
	s_lshl_b32 s1, s8, 1
	v_lshl_add_u64 v[130:131], s[2:3], 0, v[10:11]
	s_add_i32 s3, s1, 3
	s_add_i32 s2, s1, -1
	s_min_u32 s24, s3, s20
	v_mov_b64_e32 v[8:9], s[56:57]
	s_cmp_lg_u32 s8, 0
	v_mad_u64_u32 v[8:9], s[6:7], v122, s87, v[8:9]
	s_cselect_b32 s2, s2, 0
	v_mad_i32_i24 v9, v123, s87, v9
	s_lshl_b32 s8, s2, 7
	v_mov_b32_e32 v0, s19
	v_lshl_add_u64 v[8:9], v[8:9], 0, v[10:11]
	s_ashr_i32 s3, s2, 31
	v_mad_u64_u32 v[10:11], s[6:7], s8, v0, v[130:131]
	v_lshl_add_u64 v[132:133], v[130:131], 0, s[40:41]
	s_lshr_b64 s[6:7], s[2:3], 25
	v_bfe_u32 v7, v4, 3, 5
	s_mul_i32 s3, s6, s19
	v_mad_u64_u32 v[12:13], s[6:7], s8, v0, v[132:133]
	v_lshlrev_b32_e32 v0, 4, v4
	v_lshlrev_b32_e32 v20, 1, v7
	v_bfe_u32 v6, v4, 5, 1
	v_and_b32_e32 v19, 0x70, v0
	v_mul_u32_u24_e32 v0, s19, v20
	v_lshlrev_b32_e32 v128, 4, v6
	v_mov_b32_e32 v129, v1
	v_add_u32_e32 v11, s3, v11
	v_or_b32_e32 v0, v0, v19
	v_lshl_add_u64 v[8:9], v[8:9], 0, v[128:129]
	v_add_u32_e32 v13, s3, v13
	v_lshl_add_u64 v[14:15], v[10:11], 0, v[0:1]
	global_load_dwordx4 v[82:85], v[8:9], off
	global_load_dwordx4 v[86:89], v[8:9], off offset:32
	v_lshl_add_u64 v[16:17], v[12:13], 0, v[0:1]
	global_load_dwordx4 v[98:101], v[14:15], off offset:2048
	global_load_dwordx4 v[102:105], v[16:17], off
	v_mov_b32_e32 v14, s23
	v_mad_u32_u24 v14, v20, s19, v14
	v_or_b32_e32 v134, v14, v19
	v_mov_b32_e32 v135, v1
	v_lshl_add_u64 v[10:11], v[10:11], 0, v[134:135]
	v_lshl_add_u64 v[12:13], v[12:13], 0, v[134:135]
	global_load_dwordx4 v[106:109], v[10:11], off offset:2048
	global_load_dwordx4 v[110:113], v[12:13], off
	global_load_dwordx4 v[90:93], v[8:9], off offset:64
	global_load_dwordx4 v[94:97], v[8:9], off offset:96
	s_mov_b32 s3, 0xfc00
	v_mad_i32_i24 v127, v18, s3, 0
	v_add_u32_e32 v145, v127, v19
	s_add_i32 s3, s2, 1
	v_mad_u32_u24 v8, v7, s88, v145
	s_cmp_ge_u32 s3, s24
	v_mad_u32_u24 v9, v7, s51, v145
	s_add_i32 s3, s2, 1
	s_lshl_b32 s8, s3, 7
	v_mov_b32_e32 v10, s19
	v_mad_u64_u32 v[12:13], s[6:7], s8, v10, v[130:131]
	v_mad_u64_u32 v[14:15], s[6:7], s8, v10, v[132:133]
	v_lshl_add_u64 v[16:17], v[12:13], 0, v[0:1]
	v_lshl_add_u64 v[12:13], v[12:13], 0, v[134:135]
	global_load_dwordx4 v[50:53], v[16:17], off offset:2048
	v_lshl_add_u64 v[16:17], v[14:15], 0, v[0:1]
	v_lshl_add_u64 v[14:15], v[14:15], 0, v[134:135]
	global_load_dwordx4 v[54:57], v[16:17], off
	global_load_dwordx4 v[58:61], v[12:13], off offset:2048
	global_load_dwordx4 v[62:65], v[14:15], off
	s_add_i32 s3, s2, 2
	s_lshl_b32 s8, s3, 7
	v_mov_b32_e32 v10, s19
	v_mad_u64_u32 v[12:13], s[6:7], s8, v10, v[130:131]
	v_mad_u64_u32 v[14:15], s[6:7], s8, v10, v[132:133]
	v_lshl_add_u64 v[16:17], v[12:13], 0, v[0:1]
	v_lshl_add_u64 v[12:13], v[12:13], 0, v[134:135]
	global_load_dwordx4 v[66:69], v[16:17], off offset:2048
	v_lshl_add_u64 v[16:17], v[14:15], 0, v[0:1]
	v_lshl_add_u64 v[14:15], v[14:15], 0, v[134:135]
	global_load_dwordx4 v[70:73], v[16:17], off
	global_load_dwordx4 v[74:77], v[12:13], off offset:2048
	global_load_dwordx4 v[78:81], v[14:15], off
	s_add_i32 s3, s2, 3
	s_cmp_ge_u32 s3, s24
	s_cbranch_scc1 .Ldil3_noD
	s_add_i32 s3, s2, 3
	s_lshl_b32 s8, s3, 7
	v_mov_b32_e32 v10, s19
	v_mad_u64_u32 v[12:13], s[6:7], s8, v10, v[130:131]
	v_mad_u64_u32 v[14:15], s[6:7], s8, v10, v[132:133]
	v_lshl_add_u64 v[16:17], v[12:13], 0, v[0:1]
	v_lshl_add_u64 v[12:13], v[12:13], 0, v[134:135]
	global_load_dwordx4 v[214:217], v[16:17], off offset:2048
	v_lshl_add_u64 v[16:17], v[14:15], 0, v[0:1]
	v_lshl_add_u64 v[14:15], v[14:15], 0, v[134:135]
	global_load_dwordx4 v[218:221], v[16:17], off
	global_load_dwordx4 v[222:225], v[12:13], off offset:2048
	global_load_dwordx4 v[226:229], v[14:15], off
	s_waitcnt vmcnt(14)
	ds_write_b128 v8, v[98:101]
	ds_write_b128 v9, v[102:105] offset:9216
	ds_write_b128 v8, v[106:109] offset:4608
	ds_write_b128 v9, v[110:113] offset:15360
	s_waitcnt vmcnt(8)
	ds_write_b128 v8, v[50:53] offset:21504
	ds_write_b128 v9, v[54:57] offset:30720
	ds_write_b128 v8, v[58:61] offset:26112
	ds_write_b128 v9, v[62:65] offset:36864
	s_waitcnt vmcnt(4)
	ds_write_b128 v8, v[66:69] offset:43008
	ds_write_b128 v9, v[70:73] offset:52224
	ds_write_b128 v8, v[74:77] offset:47616
	ds_write_b128 v9, v[78:81] offset:58368
	s_mov_b32 s7, 1
	s_branch .Ldil3_staged
.Ldil3_noD:
	s_waitcnt vmcnt(10)
	ds_write_b128 v8, v[98:101]
	ds_write_b128 v9, v[102:105] offset:9216
	ds_write_b128 v8, v[106:109] offset:4608
	ds_write_b128 v9, v[110:113] offset:15360
	s_waitcnt vmcnt(4)
	ds_write_b128 v8, v[50:53] offset:21504
	ds_write_b128 v9, v[54:57] offset:30720
	ds_write_b128 v8, v[58:61] offset:26112
	ds_write_b128 v9, v[62:65] offset:36864
	s_waitcnt vmcnt(0)
	ds_write_b128 v8, v[66:69] offset:43008
	ds_write_b128 v9, v[70:73] offset:52224
	ds_write_b128 v8, v[74:77] offset:47616
	ds_write_b128 v9, v[78:81] offset:58368
	s_mov_b32 s7, 0
.Ldil3_staged:
.LBB0_289:
	v_and_b32_e32 v144, 63, v4
	s_cmp_ge_i32 s2, s24
	v_lshlrev_b32_e32 v129, 2, v6
	s_cbranch_scc1 .LBB0_304
	v_lshrrev_b32_e32 v5, 1, v5
	v_or_b32_e32 v6, s1, v5
	v_add_u32_e32 v148, -1, v6
	v_add_u32_e32 v149, 1, v6
	v_lshrrev_b32_e32 v6, 2, v4
	v_and_or_b32 v6, v6, 3, v129
	v_mul_u32_u24_e32 v151, 0xc0, v6
	v_and_b32_e32 v4, 16, v4
	v_lshlrev_b32_e32 v6, 2, v144
	v_and_or_b32 v4, v6, 12, v4
	v_lshlrev_b32_e32 v152, 1, v4
	v_add3_u32 v4, v5, s1, -1
	v_max_i32_e32 v4, s2, v4
	s_add_i32 s1, s0, 0xffffff84
	v_subrev_u32_e32 v153, s2, v4
	v_add3_u32 v4, s1, v3, v2
	v_sub_u32_e32 v4, v4, v129
	s_lshl_b32 s1, s2, 6
	v_subrev_u32_e32 v154, s1, v4
	s_addk_i32 s1, 0x41
	v_or_b32_e32 v4, s1, v129
	v_mul_u32_u24_e32 v150, 0x90, v2
	v_sub_u32_e32 v2, v4, v2
	v_sub_u32_e32 v2, v2, v3
	v_mov_b32_e32 v156, 0
	v_mul_u32_u24_e32 v146, 0x90, v7
	v_mul_u32_u24_e32 v147, 0xc0, v7
	v_subrev_u32_e32 v155, s0, v2
	s_mov_b32 s3, 0
	v_mov_b32_e32 v2, v1
	v_mov_b32_e32 v3, v1
	v_mov_b32_e32 v4, v1
	v_mov_b32_e32 v5, v1
	v_mov_b32_e32 v6, v1
	v_mov_b32_e32 v7, v1
	v_mov_b32_e32 v8, v1
	v_mov_b32_e32 v9, v1
	v_mov_b32_e32 v10, v1
	v_mov_b32_e32 v11, v1
	v_mov_b32_e32 v12, v1
	v_mov_b32_e32 v13, v1
	v_mov_b32_e32 v14, v1
	v_mov_b32_e32 v15, v1
	v_mov_b32_e32 v16, v1
	v_mov_b32_e32 v17, v1
	v_mov_b32_e32 v18, v1
	v_mov_b32_e32 v19, v1
	v_mov_b32_e32 v20, v1
	v_mov_b32_e32 v21, v1
	v_mov_b32_e32 v22, v1
	v_mov_b32_e32 v23, v1
	v_mov_b32_e32 v24, v1
	v_mov_b32_e32 v25, v1
	v_mov_b32_e32 v26, v1
	v_mov_b32_e32 v27, v1
	v_mov_b32_e32 v28, v1
	v_mov_b32_e32 v29, v1
	v_mov_b32_e32 v30, v1
	v_mov_b32_e32 v31, v1
	v_mov_b32_e32 v32, v1
	v_mov_b32_e32 v33, v1
	v_mov_b32_e32 v157, 0
	v_mov_b32_e32 v34, 0
	v_mov_b32_e32 v35, v156
	v_mov_b32_e32 v36, v156
	v_mov_b32_e32 v37, v156
	v_mov_b32_e32 v38, v156
	v_mov_b32_e32 v39, v156
	v_mov_b32_e32 v40, v156
	v_mov_b32_e32 v41, v156
	v_mov_b32_e32 v42, v156
	v_mov_b32_e32 v43, v156
	v_mov_b32_e32 v44, v156
	v_mov_b32_e32 v45, v156
	v_mov_b32_e32 v46, v156
	v_mov_b32_e32 v47, v156
	v_mov_b32_e32 v48, v156
	v_mov_b32_e32 v49, v156
	s_branch .LBB0_292
.LBB0_292:
	v_readfirstlane_b32 s3, v153
	s_mov_b32 s6, 0
	s_lshl_b32 s0, s3, 6
	v_subrev_u32_e32 v154, s0, v154
	v_add_u32_e32 v155, s0, v155
	s_waitcnt lgkmcnt(0)
	s_barrier
.Ldil3_loop:
	s_add_i32 s25, s2, s3
	v_readfirstlane_b32 s0, v149
	s_add_i32 s1, s24, -1
	s_min_i32 s0, s0, s1
	s_cmp_gt_i32 s25, s0
	s_cbranch_scc1 .LBB0_300
	s_cmp_eq_u32 s3, 3
	s_cselect_b32 s26, 0, s3
	s_mul_i32 s0, s26, 0x5400
	v_add_u32_e32 v54, s0, v127
	v_add3_u32 v55, v54, v150, v128
	ds_read_b128 v[50:53], v55
	ds_read_b128 v[114:117], v55 offset:32
	ds_read_b128 v[118:121], v55 offset:4608
	ds_read_b128 v[136:139], v55 offset:4640
	ds_read_b128 v[140:143], v55 offset:64
	ds_read_b128 v[182:185], v55 offset:96
	ds_read_b128 v[186:189], v55 offset:4672
	ds_read_b128 v[190:193], v55 offset:4704
	v_cmp_eq_u32_e64 s[8:9], s3, v153
	v_cmp_ne_u32_e32 vcc, s3, v153
	v_add_u32_e32 v200, v54, v151
	s_setprio 1
	s_waitcnt lgkmcnt(7)
	v_mfma_f32_32x32x16_bf16 v[66:81], v[50:53], v[82:85], v[34:49]
	s_waitcnt lgkmcnt(6)
	v_mfma_f32_32x32x16_bf16 v[66:81], v[114:117], v[86:89], v[66:81]
	s_waitcnt lgkmcnt(5)
	v_mfma_f32_32x32x16_bf16 v[50:65], v[118:121], v[82:85], v[34:49]
	s_waitcnt lgkmcnt(4)
	v_mfma_f32_32x32x16_bf16 v[50:65], v[136:139], v[86:89], v[50:65]
	s_waitcnt lgkmcnt(3)
	v_mfma_f32_32x32x16_bf16 v[66:81], v[140:143], v[90:93], v[66:81]
	s_waitcnt lgkmcnt(1)
	v_mfma_f32_32x32x16_bf16 v[50:65], v[186:189], v[90:93], v[50:65]
	v_mfma_f32_32x32x16_bf16 v[66:81], v[182:185], v[94:97], v[66:81]
	v_add_u32_e32 v182, v200, v152
	s_waitcnt lgkmcnt(0)
	v_mfma_f32_32x32x16_bf16 v[50:65], v[190:193], v[94:97], v[50:65]
	s_setprio 0
	ds_read_b64_tr_b16 v[118:119], v182 offset:9216
	ds_read_b64_tr_b16 v[120:121], v182 offset:10752
	ds_read_b64_tr_b16 v[116:117], v182 offset:10816
	ds_read_b64_tr_b16 v[114:115], v182 offset:9280
	v_add_u32_e32 v136, 59, v154
	v_cmp_lt_u32_e64 s[0:1], s60, v136
	s_mov_b64 s[10:11], s[8:9]
	s_nop 0
	v_cndmask_b32_e64 v136, v198, v66, s[0:1]
	s_movk_i32 s0, 0x81
	v_cmp_gt_u32_e64 s[0:1], s0, v155
	v_add_u32_e32 v66, 57, v154
	s_nop 0
	v_cndmask_b32_e64 v137, v198, v67, s[0:1]
	v_cmp_lt_u32_e64 s[0:1], s60, v66
	v_add_u32_e32 v66, 56, v154
	s_nop 0
	v_cndmask_b32_e64 v138, v198, v68, s[0:1]
	v_cmp_lt_u32_e64 s[0:1], s60, v66
	v_add_u32_e32 v66, 51, v154
	s_nop 0
	v_cndmask_b32_e64 v139, v198, v69, s[0:1]
	v_cmp_lt_u32_e64 s[0:1], s60, v66
	v_add_u32_e32 v66, 50, v154
	s_nop 0
	v_cndmask_b32_e64 v142, v198, v70, s[0:1]
	v_cmp_lt_u32_e64 s[0:1], s60, v66
	v_add_u32_e32 v66, 49, v154
	s_nop 0
	v_cndmask_b32_e64 v143, v198, v71, s[0:1]
	v_cmp_lt_u32_e64 s[0:1], s60, v66
	v_add_u32_e32 v66, 48, v154
	s_nop 0
	v_cndmask_b32_e64 v140, v198, v72, s[0:1]
	v_cmp_lt_u32_e64 s[0:1], s60, v66
	v_add_u32_e32 v66, 43, v154
	s_nop 0
	v_cndmask_b32_e64 v141, v198, v73, s[0:1]
	v_cmp_lt_u32_e64 s[0:1], s60, v66
	v_add_u32_e32 v66, 42, v154
	s_nop 0
	v_cndmask_b32_e64 v68, v198, v74, s[0:1]
	v_cmp_lt_u32_e64 s[0:1], s60, v66
	v_add_u32_e32 v66, 41, v154
	s_nop 0
	v_cndmask_b32_e64 v69, v198, v75, s[0:1]
	v_cmp_lt_u32_e64 s[0:1], s60, v66
	v_add_u32_e32 v66, 40, v154
	s_nop 0
	v_cndmask_b32_e64 v70, v198, v76, s[0:1]
	v_cmp_lt_u32_e64 s[0:1], s60, v66
	v_add_u32_e32 v66, 35, v154
	s_nop 0
	v_cndmask_b32_e64 v71, v198, v77, s[0:1]
	v_cmp_lt_u32_e64 s[0:1], s60, v66
	v_add_u32_e32 v66, 34, v154
	s_nop 0
	v_cndmask_b32_e64 v74, v198, v78, s[0:1]
	v_cmp_lt_u32_e64 s[0:1], s60, v66
	v_add_u32_e32 v66, 33, v154
	s_nop 0
	v_cndmask_b32_e64 v75, v198, v79, s[0:1]
	v_cmp_lt_u32_e64 s[0:1], s60, v66
	v_add_u32_e32 v66, 32, v154
	s_nop 0
	v_cndmask_b32_e64 v76, v198, v80, s[0:1]
	v_cmp_lt_u32_e64 s[0:1], s60, v66
	v_add_u32_e32 v66, 27, v154
	s_nop 0
	v_cndmask_b32_e64 v77, v198, v81, s[0:1]
	v_cmp_lt_u32_e64 s[0:1], s60, v66
	s_nop 1
	v_cndmask_b32_e64 v66, v198, v50, s[0:1]
	v_add_u32_e32 v50, 26, v154
	v_cmp_lt_u32_e64 s[0:1], s60, v50
	v_add_u32_e32 v50, 25, v154
	s_nop 0
	v_cndmask_b32_e64 v67, v198, v51, s[0:1]
	v_cmp_lt_u32_e64 s[0:1], s60, v50
	v_add_u32_e32 v50, 24, v154
	v_add_u32_e32 v51, 10, v154
	v_cndmask_b32_e64 v52, v198, v52, s[0:1]
	v_cmp_lt_u32_e64 s[0:1], s60, v50
	v_add_u32_e32 v50, 19, v154
	s_nop 0
	v_cndmask_b32_e64 v53, v198, v53, s[0:1]
	v_cmp_lt_u32_e64 s[0:1], s60, v50
	v_add_u32_e32 v50, 18, v154
	s_nop 0
	v_cndmask_b32_e64 v72, v198, v54, s[0:1]
	v_cmp_lt_u32_e64 s[0:1], s60, v50
	v_add_u32_e32 v50, 17, v154
	v_add_u32_e32 v54, 9, v154
	v_cndmask_b32_e64 v73, v198, v55, s[0:1]
	v_cmp_lt_u32_e64 s[0:1], s60, v50
	v_add_u32_e32 v50, 16, v154
	v_add_u32_e32 v55, 8, v154
	v_cndmask_b32_e64 v56, v198, v56, s[0:1]
	v_cmp_lt_u32_e64 s[0:1], s60, v50
	v_add_u32_e32 v50, 11, v154
	s_nop 0
	v_cndmask_b32_e64 v57, v198, v57, s[0:1]
	v_cmp_lt_u32_e64 s[0:1], s60, v50
	s_nop 1
	v_cndmask_b32_e64 v50, v198, v58, s[0:1]
	v_cmp_lt_u32_e64 s[0:1], s60, v51
	v_add_u32_e32 v58, 3, v154
	s_nop 0
	v_cndmask_b32_e64 v51, v198, v59, s[0:1]
	v_cmp_lt_u32_e64 s[0:1], s60, v54
	v_add_u32_e32 v59, 2, v154
	s_nop 0
	v_cndmask_b32_e64 v54, v198, v60, s[0:1]
	v_cmp_lt_u32_e64 s[0:1], s60, v55
	v_add_u32_e32 v60, 1, v154
	s_nop 0
	v_cndmask_b32_e64 v55, v198, v61, s[0:1]
	v_cmp_lt_u32_e64 s[0:1], s60, v58
	s_nop 1
	v_cndmask_b32_e64 v58, v198, v62, s[0:1]
	v_cmp_lt_u32_e64 s[0:1], s60, v59
	v_max3_f32 v62, v136, v66, v137
	v_max3_f32 v62, v62, v139, v53
	v_cndmask_b32_e64 v59, v198, v63, s[0:1]
	v_cmp_lt_u32_e64 s[0:1], s60, v60
	v_max_f32_e32 v63, v138, v138
	v_max3_f32 v62, v62, v143, v73
	v_cndmask_b32_e64 v60, v198, v64, s[0:1]
	v_max_f32_e32 v64, v67, v67
	v_max_f32_e32 v63, v64, v63
	v_max3_f32 v63, v63, v52, v142
	v_max3_f32 v63, v63, v72, v140
	v_max3_f32 v63, v63, v56, v68
	v_max3_f32 v62, v62, v141, v57
	v_max3_f32 v63, v63, v50, v70
	v_cmp_lt_u32_e64 s[0:1], s60, v154
	v_max3_f32 v62, v62, v69, v51
	v_max3_f32 v63, v63, v54, v74
	v_cndmask_b32_e64 v61, v198, v65, s[0:1]
	v_max3_f32 v62, v62, v71, v55
	v_max3_f32 v63, v63, v58, v76
	v_max3_f32 v62, v62, v75, v59
	v_max3_f32 v63, v63, v60, v61
	v_max3_f32 v62, v62, v77, v63
	v_mov_b32_e32 v63, v62
	s_nop 1
	v_permlane32_swap_b32_e32 v62, v63
	v_max_f32_e32 v63, v63, v63
	v_max_f32_e32 v62, v62, v62
	v_max_f32_e32 v62, v62, v63
	s_and_saveexec_b64 s[16:17], vcc
	v_cmp_lt_f32_e64 s[0:1], s61, v62
	s_cmp_lg_u64 s[0:1], 0
	s_cselect_b64 s[0:1], -1, 0
	s_andn2_b64 s[10:11], s[8:9], exec
	s_and_b64 s[0:1], s[0:1], exec
	s_or_b64 s[10:11], s[10:11], s[0:1]
	s_or_b64 exec, exec, s[16:17]
	s_and_saveexec_b64 s[0:1], s[10:11]
	s_cbranch_execz .LBB0_299
	v_max_f32_e32 v34, v62, v62
	v_max_f32_e32 v34, 0, v34
	s_and_saveexec_b64 s[10:11], vcc
	s_cbranch_execz .LBB0_298
	v_exp_f32_e64 v36, -v34
	s_nop 0
	v_mul_f32_e32 v156, v156, v36
	v_pk_mul_f32 v[32:33], v[32:33], v[36:37] op_sel_hi:[1,0]
	v_pk_mul_f32 v[30:31], v[30:31], v[36:37] op_sel_hi:[1,0]
	v_pk_mul_f32 v[28:29], v[28:29], v[36:37] op_sel_hi:[1,0]
	v_pk_mul_f32 v[26:27], v[26:27], v[36:37] op_sel_hi:[1,0]
	v_pk_mul_f32 v[24:25], v[24:25], v[36:37] op_sel_hi:[1,0]
	v_pk_mul_f32 v[22:23], v[22:23], v[36:37] op_sel_hi:[1,0]
	v_pk_mul_f32 v[20:21], v[20:21], v[36:37] op_sel_hi:[1,0]
	v_pk_mul_f32 v[18:19], v[18:19], v[36:37] op_sel_hi:[1,0]
	v_pk_mul_f32 v[16:17], v[16:17], v[36:37] op_sel_hi:[1,0]
	v_pk_mul_f32 v[14:15], v[14:15], v[36:37] op_sel_hi:[1,0]
	v_pk_mul_f32 v[12:13], v[12:13], v[36:37] op_sel_hi:[1,0]
	v_pk_mul_f32 v[10:11], v[10:11], v[36:37] op_sel_hi:[1,0]
	v_pk_mul_f32 v[8:9], v[8:9], v[36:37] op_sel_hi:[1,0]
	v_pk_mul_f32 v[6:7], v[6:7], v[36:37] op_sel_hi:[1,0]
	v_pk_mul_f32 v[4:5], v[4:5], v[36:37] op_sel_hi:[1,0]
	v_pk_mul_f32 v[2:3], v[2:3], v[36:37] op_sel_hi:[1,0]

.LBB0_300:
	s_cmp_lg_u32 s6, 0
	s_cbranch_scc1 .Ldil3_p1
	s_waitcnt lgkmcnt(0)
	s_barrier
	s_cmp_eq_u32 s7, 0
	s_cbranch_scc1 .Ldil3_adv
	v_add_u32_e32 v51, v145, v146
	v_add_u32_e32 v50, v145, v147
	s_waitcnt vmcnt(0)
	ds_write_b128 v51, v[214:217]
	ds_write_b128 v50, v[218:221] offset:9216
	ds_write_b128 v51, v[222:225] offset:4608
	ds_write_b128 v50, v[226:229] offset:15360
	s_branch .Ldil3_adv
.Ldil3_p1:
	s_cmp_lg_u32 s6, 1
	s_cbranch_scc1 .Ldil3_adv
	s_waitcnt lgkmcnt(0)
	s_barrier
.Ldil3_adv:
	s_add_i32 s3, s3, 1
	s_add_i32 s6, s6, 1
	v_subrev_u32_e32 v154, 64, v154
	v_add_u32_e32 v155, 64, v155
	s_cmp_lt_u32 s6, 3
	s_cbranch_scc1 .Ldil3_loop
	s_branch .LBB0_305
